# P7 K-loop back-edge rotation: counter and exit test moved ahead of the loop's last barrier; loop-head address SALU moved after the first fragment reads
# speedup vs baseline: 1.0040x; 1.0040x over previous
; #define PG8_STAGE(bufoff, gbase, voff) do { _Pragma("unroll") for (int _i = 0; _i < 2; ++_i) \
;         __builtin_amdgcn_global_load_lds((const unsigned*)((const char*)(gbase) + (voff)[_i]), (PG8_LAS unsigned*)(lds + (bufoff) + ldsw + _i * 8192), 16, 0, 0); } while (0)
; #define PG8_LDA(dst, b, h) do { _Pragma("unroll") for (int m = 0; m < 4; ++m) _Pragma("unroll") for (int k = 0; k < 2; ++k) dst[m][k] = *(const PG8_LAS bf16x8*)(lds + PG8_SA(b, h) + aoff + m * 2048 + k * 1024); } while (0)
; #define PG8_LDB(dst, b, h) do { _Pragma("unroll") for (int n = 0; n < 2; ++n) _Pragma("unroll") for (int k = 0; k < 2; ++k) dst[n][k] = *(const PG8_LAS bf16x8*)(lds + PG8_SB(b, h) + boff + n * 2048 + k * 1024); } while (0)
; #define PG8_MMA(ai, bj, At, Bt) do { __builtin_amdgcn_s_setprio(1); _Pragma("unroll") for (int m = 0; m < 4; ++m) _Pragma("unroll") for (int n = 0; n < 2; ++n) _Pragma("unroll") for (int k = 0; k < 2; ++k) \
;         acc[ai][bj][m][n] = __builtin_amdgcn_mfma_f32_16x16x32_bf16(Bt[n][k], At[m][k], acc[ai][bj][m][n], 0, 0, 0); __builtin_amdgcn_s_setprio(0); } while (0)
; #define PG8_WAIT_V(n) asm volatile("s_waitcnt vmcnt(" #n ")" ::: "memory")
; #define PG8_WAIT_L(n) asm volatile("s_waitcnt lgkmcnt(" #n ")" ::: "memory")
; #define PG8_BAR __builtin_amdgcn_s_barrier()
; #define PG8_SCHED __builtin_amdgcn_sched_barrier(0)
; template <class Epi, class Sched, bool ALIGN_EPI = false, bool SP2 = false>
; __device__ __forceinline__ void gemm_phase(PG8_LAS unsigned char* lds, const Gemm g, const Sched& S, const Epi& E) {
;     ...
;         for (int t = 0; t < nt; t += 2) {
;             const bool last = (t == nt - 2);
;             const char* a1 = cA + (size_t)(t + 1) * kstep;
;             const char* a2 = last ? nA : cA + (size_t)(t + 2) * kstep; const char* b2 = last ? nB : cB + (size_t)(t + 2) * kstep;
;             const char* a3 = a2 + kstep; const char* b3 = b2 + kstep;
;             if (last && has_next) S.a_ready(nxt);
;             if constexpr (SP2) {
;             PG8_LDB(B0, 0, 0); PG8_LDB(B1, 0, 1); PG8_SCHED; PG8_LDA(At, 0, 0); PG8_STAGE(PG8_SA(1, 1), a1 + hstepA, voffA);
;             PG8_WAIT_V(8); PG8_WAIT_L(0); PG8_BAR; PG8_MMA(0, 0, At, B0); PG8_MMA(0, 1, At, B1); PG8_BAR; PG8_SCHED;
.Lp7_prio_done:
.LBB0_583:
	s_add_i32 s17, 0, 0x10000
	v_add_u32_e32 v132, s17, v159
	s_add_i32 s66, 0, 0x14000
	ds_read_b128 v[128:131], v132
	ds_read_b128 v[154:157], v132 offset:1024
	ds_read_b128 v[170:173], v132 offset:2048
	ds_read_b128 v[174:177], v132 offset:3072
	v_add_u32_e32 v132, s66, v159
	ds_read_b128 v[178:181], v132
	ds_read_b128 v[182:185], v132 offset:1024
	ds_read_b128 v[186:189], v132 offset:2048
	ds_read_b128 v[190:193], v132 offset:3072
	s_add_u32 s12, s10, 0xfff80080
	s_addc_u32 s13, s11, -1
	s_cmp_eq_u32 s16, 28
	s_cselect_b32 s35, s27, s13
	s_cselect_b32 s34, s62, s12
	s_cselect_b32 s13, s25, vcc_hi
	s_cselect_b32 s12, s91, vcc_lo
	v_lshl_add_u64 v[226:227], s[10:11], 0, v[150:151]
	s_add_i32 m0, s41, 0xc000
	ds_read_b128 v[194:197], v161
	ds_read_b128 v[198:201], v161 offset:1024
	ds_read_b128 v[202:205], v161 offset:2048
	ds_read_b128 v[206:209], v161 offset:3072
	ds_read_b128 v[210:213], v161 offset:4096
	ds_read_b128 v[214:217], v161 offset:5120
	ds_read_b128 v[218:221], v161 offset:6144
	ds_read_b128 v[222:225], v161 offset:7168
	global_load_lds_dwordx4 v[226:227], off
	v_lshl_add_u64 v[226:227], s[10:11], 0, v[152:153]
	s_add_i32 m0, s41, 0xe000
	s_nop 0
	global_load_lds_dwordx4 v[226:227], off
	s_waitcnt vmcnt(8)
	s_waitcnt lgkmcnt(0)
	s_barrier
	s_waitcnt lgkmcnt(0)
	v_mfma_f32_16x16x32_bf16 v[124:127], v[128:131], v[194:197], v[124:127]
	v_mfma_f32_16x16x32_bf16 v[120:123], v[170:173], v[194:197], v[120:123]
	v_mfma_f32_16x16x32_bf16 v[108:111], v[128:131], v[202:205], v[108:111]
	v_mfma_f32_16x16x32_bf16 v[104:107], v[170:173], v[202:205], v[104:107]
	v_mfma_f32_16x16x32_bf16 v[92:95], v[128:131], v[210:213], v[92:95]
	v_mfma_f32_16x16x32_bf16 v[88:91], v[170:173], v[210:213], v[88:91]
	v_mfma_f32_16x16x32_bf16 v[76:79], v[128:131], v[218:221], v[76:79]
	v_mfma_f32_16x16x32_bf16 v[72:75], v[170:173], v[218:221], v[72:75]
	v_mfma_f32_16x16x32_bf16 v[124:127], v[154:157], v[198:201], v[124:127]
	v_mfma_f32_16x16x32_bf16 v[120:123], v[174:177], v[198:201], v[120:123]
	v_mfma_f32_16x16x32_bf16 v[108:111], v[154:157], v[206:209], v[108:111]
	v_mfma_f32_16x16x32_bf16 v[104:107], v[174:177], v[206:209], v[104:107]
	v_mfma_f32_16x16x32_bf16 v[92:95], v[154:157], v[214:217], v[92:95]
	v_mfma_f32_16x16x32_bf16 v[88:91], v[174:177], v[214:217], v[88:91]
	v_mfma_f32_16x16x32_bf16 v[76:79], v[154:157], v[222:225], v[76:79]
	v_mfma_f32_16x16x32_bf16 v[72:75], v[174:177], v[222:225], v[72:75]
	v_mfma_f32_16x16x32_bf16 v[116:119], v[178:181], v[194:197], v[116:119]
	v_mfma_f32_16x16x32_bf16 v[112:115], v[186:189], v[194:197], v[112:115]
	v_mfma_f32_16x16x32_bf16 v[100:103], v[178:181], v[202:205], v[100:103]
	v_mfma_f32_16x16x32_bf16 v[96:99], v[186:189], v[202:205], v[96:99]
	v_mfma_f32_16x16x32_bf16 v[84:87], v[178:181], v[210:213], v[84:87]
	v_mfma_f32_16x16x32_bf16 v[80:83], v[186:189], v[210:213], v[80:83]
	v_mfma_f32_16x16x32_bf16 v[68:71], v[178:181], v[218:221], v[68:71]
	v_mfma_f32_16x16x32_bf16 v[64:67], v[186:189], v[218:221], v[64:67]
	v_mfma_f32_16x16x32_bf16 v[116:119], v[182:185], v[198:201], v[116:119]
	v_mfma_f32_16x16x32_bf16 v[112:115], v[190:193], v[198:201], v[112:115]
	v_mfma_f32_16x16x32_bf16 v[100:103], v[182:185], v[206:209], v[100:103]
	v_mfma_f32_16x16x32_bf16 v[96:99], v[190:193], v[206:209], v[96:99]
	v_mfma_f32_16x16x32_bf16 v[84:87], v[182:185], v[214:217], v[84:87]
	v_mfma_f32_16x16x32_bf16 v[80:83], v[190:193], v[214:217], v[80:83]
	v_mfma_f32_16x16x32_bf16 v[68:71], v[182:185], v[222:225], v[68:71]
	v_mfma_f32_16x16x32_bf16 v[64:67], v[190:193], v[222:225], v[64:67]
	s_barrier
	s_add_i32 s17, s17, s40
	v_lshl_add_u64 v[226:227], s[12:13], 0, v[142:143]
	s_mov_b32 m0, s17
	ds_read_b128 v[194:197], v161 offset:16384
	ds_read_b128 v[198:201], v161 offset:17408
	ds_read_b128 v[202:205], v161 offset:18432
	ds_read_b128 v[206:209], v161 offset:19456
	ds_read_b128 v[210:213], v161 offset:20480
	ds_read_b128 v[214:217], v161 offset:21504
	ds_read_b128 v[218:221], v161 offset:22528
	ds_read_b128 v[222:225], v161 offset:23552
	global_load_lds_dwordx4 v[226:227], off
	s_add_i32 m0, s17, 0x2000
	s_add_u32 s64, s12, 0x80000
	v_lshl_add_u64 v[228:229], s[12:13], 0, v[138:139]
	s_addc_u32 s65, s13, 0
	s_add_i32 s17, s66, s40
	global_load_lds_dwordx4 v[228:229], off
	v_lshl_add_u64 v[230:231], s[64:65], 0, v[142:143]
	s_mov_b32 m0, s17
	v_lshl_add_u64 v[232:233], s[34:35], 0, v[140:141]
	global_load_lds_dwordx4 v[230:231], off
	v_lshl_add_u64 v[230:231], s[64:65], 0, v[138:139]
	s_add_i32 m0, s17, 0x2000
	s_nop 0
	global_load_lds_dwordx4 v[230:231], off
	v_lshl_add_u64 v[230:231], s[34:35], 0, v[144:145]
	s_mov_b32 m0, s41
	s_nop 0
	global_load_lds_dwordx4 v[230:231], off
	s_mov_b32 m0, s58
	s_nop 0
	global_load_lds_dwordx4 v[232:233], off
	s_waitcnt vmcnt(8)
	s_waitcnt lgkmcnt(0)
	s_barrier
; #define PG8_STAGE(bufoff, gbase, voff) do { _Pragma("unroll") for (int _i = 0; _i < 2; ++_i) \
;         __builtin_amdgcn_global_load_lds((const unsigned*)((const char*)(gbase) + (voff)[_i]), (PG8_LAS unsigned*)(lds + (bufoff) + ldsw + _i * 8192), 16, 0, 0); } while (0)
; #define PG8_LDA(dst, b, h) do { _Pragma("unroll") for (int m = 0; m < 4; ++m) _Pragma("unroll") for (int k = 0; k < 2; ++k) dst[m][k] = *(const PG8_LAS bf16x8*)(lds + PG8_SA(b, h) + aoff + m * 2048 + k * 1024); } while (0)
; #define PG8_LDB(dst, b, h) do { _Pragma("unroll") for (int n = 0; n < 2; ++n) _Pragma("unroll") for (int k = 0; k < 2; ++k) dst[n][k] = *(const PG8_LAS bf16x8*)(lds + PG8_SB(b, h) + boff + n * 2048 + k * 1024); } while (0)
; #define PG8_MMA(ai, bj, At, Bt) do { __builtin_amdgcn_s_setprio(1); _Pragma("unroll") for (int m = 0; m < 4; ++m) _Pragma("unroll") for (int n = 0; n < 2; ++n) _Pragma("unroll") for (int k = 0; k < 2; ++k) \
;         acc[ai][bj][m][n] = __builtin_amdgcn_mfma_f32_16x16x32_bf16(Bt[n][k], At[m][k], acc[ai][bj][m][n], 0, 0, 0); __builtin_amdgcn_s_setprio(0); } while (0)
; #define PG8_WAIT_V(n) asm volatile("s_waitcnt vmcnt(" #n ")" ::: "memory")
; #define PG8_WAIT_L(n) asm volatile("s_waitcnt lgkmcnt(" #n ")" ::: "memory")
; #define PG8_BAR __builtin_amdgcn_s_barrier()
; #define PG8_SCHED __builtin_amdgcn_sched_barrier(0)
; template <class Epi, class Sched, bool ALIGN_EPI = false, bool SP2 = false>
; __device__ __forceinline__ void gemm_phase(PG8_LAS unsigned char* lds, const Gemm g, const Sched& S, const Epi& E) {
;     ...
;             PG8_WAIT_V(8); PG8_WAIT_L(0); PG8_BAR; PG8_MMA(1, 0, At, B0); PG8_MMA(1, 1, At, B1); PG8_BAR; PG8_SCHED;
;             PG8_LDB(B0, 1, 0); PG8_LDB(B1, 1, 1); PG8_SCHED; PG8_LDA(At, 1, 0); PG8_STAGE(PG8_SA(0, 1), a2 + hstepA, voffA);
;             PG8_WAIT_V(8); PG8_WAIT_L(0); PG8_BAR; PG8_MMA(0, 0, At, B0); PG8_MMA(0, 1, At, B1); PG8_BAR; PG8_SCHED;
	s_waitcnt lgkmcnt(0)
	v_mfma_f32_16x16x32_bf16 v[60:63], v[128:131], v[194:197], v[60:63]
	v_mfma_f32_16x16x32_bf16 v[56:59], v[170:173], v[194:197], v[56:59]
	v_mfma_f32_16x16x32_bf16 v[44:47], v[128:131], v[202:205], v[44:47]
	v_mfma_f32_16x16x32_bf16 v[40:43], v[170:173], v[202:205], v[40:43]
	v_mfma_f32_16x16x32_bf16 v[28:31], v[128:131], v[210:213], v[28:31]
	v_mfma_f32_16x16x32_bf16 v[24:27], v[170:173], v[210:213], v[24:27]
	v_mfma_f32_16x16x32_bf16 v[12:15], v[128:131], v[218:221], v[12:15]
	v_mfma_f32_16x16x32_bf16 v[8:11], v[170:173], v[218:221], v[8:11]
	v_mfma_f32_16x16x32_bf16 v[60:63], v[154:157], v[198:201], v[60:63]
	v_mfma_f32_16x16x32_bf16 v[56:59], v[174:177], v[198:201], v[56:59]
	v_mfma_f32_16x16x32_bf16 v[44:47], v[154:157], v[206:209], v[44:47]
	v_mfma_f32_16x16x32_bf16 v[40:43], v[174:177], v[206:209], v[40:43]
	v_mfma_f32_16x16x32_bf16 v[28:31], v[154:157], v[214:217], v[28:31]
	v_mfma_f32_16x16x32_bf16 v[24:27], v[174:177], v[214:217], v[24:27]
	v_mfma_f32_16x16x32_bf16 v[12:15], v[154:157], v[222:225], v[12:15]
	v_mfma_f32_16x16x32_bf16 v[8:11], v[174:177], v[222:225], v[8:11]
	v_mfma_f32_16x16x32_bf16 v[52:55], v[178:181], v[194:197], v[52:55]
	v_mfma_f32_16x16x32_bf16 v[48:51], v[186:189], v[194:197], v[48:51]
	v_mfma_f32_16x16x32_bf16 v[36:39], v[178:181], v[202:205], v[36:39]
	v_mfma_f32_16x16x32_bf16 v[32:35], v[186:189], v[202:205], v[32:35]
	v_mfma_f32_16x16x32_bf16 v[20:23], v[178:181], v[210:213], v[20:23]
	v_mfma_f32_16x16x32_bf16 v[16:19], v[186:189], v[210:213], v[16:19]
	v_mfma_f32_16x16x32_bf16 v[4:7], v[178:181], v[218:221], v[4:7]
	v_mfma_f32_16x16x32_bf16 v[0:3], v[186:189], v[218:221], v[0:3]
	v_mfma_f32_16x16x32_bf16 v[52:55], v[182:185], v[198:201], v[52:55]
	v_mfma_f32_16x16x32_bf16 v[48:51], v[190:193], v[198:201], v[48:51]
	v_mfma_f32_16x16x32_bf16 v[36:39], v[182:185], v[206:209], v[36:39]
	v_mfma_f32_16x16x32_bf16 v[32:35], v[190:193], v[206:209], v[32:35]
	v_mfma_f32_16x16x32_bf16 v[20:23], v[182:185], v[214:217], v[20:23]
	v_mfma_f32_16x16x32_bf16 v[16:19], v[190:193], v[214:217], v[16:19]
	v_mfma_f32_16x16x32_bf16 v[4:7], v[182:185], v[222:225], v[4:7]
	v_mfma_f32_16x16x32_bf16 v[0:3], v[190:193], v[222:225], v[0:3]
	s_barrier
	s_add_i32 s17, 0, 0x18000
	v_add_u32_e32 v132, s17, v159
	s_add_i32 s64, 0, 0x1c000
	ds_read_b128 v[128:131], v132
	ds_read_b128 v[154:157], v132 offset:1024
	ds_read_b128 v[170:173], v132 offset:2048
	ds_read_b128 v[174:177], v132 offset:3072
	v_add_u32_e32 v132, s64, v159
	ds_read_b128 v[178:181], v132
	ds_read_b128 v[182:185], v132 offset:1024
	ds_read_b128 v[186:189], v132 offset:2048
	ds_read_b128 v[190:193], v132 offset:3072
	s_add_u32 s34, s34, 0x80000
	s_addc_u32 s35, s35, 0
	s_mov_b32 m0, s88
	v_lshl_add_u64 v[234:235], s[34:35], 0, v[144:145]
	ds_read_b128 v[194:197], v161 offset:32768
	ds_read_b128 v[198:201], v161 offset:33792
	ds_read_b128 v[202:205], v161 offset:34816
	ds_read_b128 v[206:209], v161 offset:35840
	ds_read_b128 v[210:213], v161 offset:36864
	ds_read_b128 v[214:217], v161 offset:37888
	ds_read_b128 v[218:221], v161 offset:38912
	ds_read_b128 v[222:225], v161 offset:39936
	global_load_lds_dwordx4 v[234:235], off
	v_lshl_add_u64 v[234:235], s[34:35], 0, v[140:141]
	s_mov_b32 m0, s89
	s_nop 0
	global_load_lds_dwordx4 v[234:235], off
	s_waitcnt vmcnt(8)
	s_waitcnt lgkmcnt(0)
	s_barrier
	s_waitcnt lgkmcnt(0)
	v_mfma_f32_16x16x32_bf16 v[124:127], v[128:131], v[194:197], v[124:127]
	v_mfma_f32_16x16x32_bf16 v[120:123], v[170:173], v[194:197], v[120:123]
	v_mfma_f32_16x16x32_bf16 v[108:111], v[128:131], v[202:205], v[108:111]
	v_mfma_f32_16x16x32_bf16 v[104:107], v[170:173], v[202:205], v[104:107]
	v_mfma_f32_16x16x32_bf16 v[92:95], v[128:131], v[210:213], v[92:95]
	v_mfma_f32_16x16x32_bf16 v[88:91], v[170:173], v[210:213], v[88:91]
	v_mfma_f32_16x16x32_bf16 v[76:79], v[128:131], v[218:221], v[76:79]
	v_mfma_f32_16x16x32_bf16 v[72:75], v[170:173], v[218:221], v[72:75]
	v_mfma_f32_16x16x32_bf16 v[124:127], v[154:157], v[198:201], v[124:127]
	v_mfma_f32_16x16x32_bf16 v[120:123], v[174:177], v[198:201], v[120:123]
	v_mfma_f32_16x16x32_bf16 v[108:111], v[154:157], v[206:209], v[108:111]
	v_mfma_f32_16x16x32_bf16 v[104:107], v[174:177], v[206:209], v[104:107]
	v_mfma_f32_16x16x32_bf16 v[92:95], v[154:157], v[214:217], v[92:95]
	v_mfma_f32_16x16x32_bf16 v[88:91], v[174:177], v[214:217], v[88:91]
	v_mfma_f32_16x16x32_bf16 v[76:79], v[154:157], v[222:225], v[76:79]
	v_mfma_f32_16x16x32_bf16 v[72:75], v[174:177], v[222:225], v[72:75]
	v_mfma_f32_16x16x32_bf16 v[116:119], v[178:181], v[194:197], v[116:119]
	v_mfma_f32_16x16x32_bf16 v[112:115], v[186:189], v[194:197], v[112:115]
	v_mfma_f32_16x16x32_bf16 v[100:103], v[178:181], v[202:205], v[100:103]
	v_mfma_f32_16x16x32_bf16 v[96:99], v[186:189], v[202:205], v[96:99]
	v_mfma_f32_16x16x32_bf16 v[84:87], v[178:181], v[210:213], v[84:87]
	v_mfma_f32_16x16x32_bf16 v[80:83], v[186:189], v[210:213], v[80:83]
	v_mfma_f32_16x16x32_bf16 v[68:71], v[178:181], v[218:221], v[68:71]
	v_mfma_f32_16x16x32_bf16 v[64:67], v[186:189], v[218:221], v[64:67]
	v_mfma_f32_16x16x32_bf16 v[116:119], v[182:185], v[198:201], v[116:119]
	v_mfma_f32_16x16x32_bf16 v[112:115], v[190:193], v[198:201], v[112:115]
	v_mfma_f32_16x16x32_bf16 v[100:103], v[182:185], v[206:209], v[100:103]
	v_mfma_f32_16x16x32_bf16 v[96:99], v[190:193], v[206:209], v[96:99]
	v_mfma_f32_16x16x32_bf16 v[84:87], v[182:185], v[214:217], v[84:87]
	v_mfma_f32_16x16x32_bf16 v[80:83], v[190:193], v[214:217], v[80:83]
	v_mfma_f32_16x16x32_bf16 v[68:71], v[182:185], v[222:225], v[68:71]
	v_mfma_f32_16x16x32_bf16 v[64:67], v[190:193], v[222:225], v[64:67]
	s_barrier
; #define PG8_STAGE(bufoff, gbase, voff) do { _Pragma("unroll") for (int _i = 0; _i < 2; ++_i) \
;         __builtin_amdgcn_global_load_lds((const unsigned*)((const char*)(gbase) + (voff)[_i]), (PG8_LAS unsigned*)(lds + (bufoff) + ldsw + _i * 8192), 16, 0, 0); } while (0)
; #define PG8_LDA(dst, b, h) do { _Pragma("unroll") for (int m = 0; m < 4; ++m) _Pragma("unroll") for (int k = 0; k < 2; ++k) dst[m][k] = *(const PG8_LAS bf16x8*)(lds + PG8_SA(b, h) + aoff + m * 2048 + k * 1024); } while (0)
; #define PG8_MMA(ai, bj, At, Bt) do { __builtin_amdgcn_s_setprio(1); _Pragma("unroll") for (int m = 0; m < 4; ++m) _Pragma("unroll") for (int n = 0; n < 2; ++n) _Pragma("unroll") for (int k = 0; k < 2; ++k) \
;         acc[ai][bj][m][n] = __builtin_amdgcn_mfma_f32_16x16x32_bf16(Bt[n][k], At[m][k], acc[ai][bj][m][n], 0, 0, 0); __builtin_amdgcn_s_setprio(0); } while (0)
; #define PG8_WAIT_V(n) asm volatile("s_waitcnt vmcnt(" #n ")" ::: "memory")
; #define PG8_WAIT_L(n) asm volatile("s_waitcnt lgkmcnt(" #n ")" ::: "memory")
; #define PG8_BAR __builtin_amdgcn_s_barrier()
; #define PG8_SCHED __builtin_amdgcn_sched_barrier(0)
; template <class Epi, class Sched, bool ALIGN_EPI = false, bool SP2 = false>
; __device__ __forceinline__ void gemm_phase(PG8_LAS unsigned char* lds, const Gemm g, const Sched& S, const Epi& E) {
;     ...
;         for (int t = 0; t < nt; t += 2) {
;     ...
;             PG8_LDA(At, 1, 1); PG8_STAGE(PG8_SB(1, 0), b3, voffB); PG8_STAGE(PG8_SB(1, 1), b3 + hstep, voffB); PG8_STAGE(PG8_SA(1, 0), a3, voffA);
;             PG8_WAIT_V(8); PG8_WAIT_L(0); PG8_BAR; PG8_MMA(1, 0, At, B0); PG8_MMA(1, 1, At, B1); PG8_BAR; PG8_SCHED;
	s_add_i32 s17, s17, s40
	v_lshl_add_u64 v[226:227], v[226:227], 0, s[68:69]
	s_mov_b32 m0, s17
	ds_read_b128 v[194:197], v161 offset:49152
	ds_read_b128 v[198:201], v161 offset:50176
	ds_read_b128 v[202:205], v161 offset:51200
	ds_read_b128 v[206:209], v161 offset:52224
	ds_read_b128 v[210:213], v161 offset:53248
	ds_read_b128 v[214:217], v161 offset:54272
	ds_read_b128 v[218:221], v161 offset:55296
	ds_read_b128 v[222:225], v161 offset:56320
	global_load_lds_dwordx4 v[226:227], off
	s_add_i32 m0, s17, 0x2000
	s_add_u32 s12, s12, 0x80080
	v_lshl_add_u64 v[226:227], v[228:229], 0, s[68:69]
	s_addc_u32 s13, s13, 0
	s_add_i32 s17, s64, s40
	global_load_lds_dwordx4 v[226:227], off
	v_lshl_add_u64 v[226:227], s[12:13], 0, v[142:143]
	s_mov_b32 m0, s17
	s_nop 0
	global_load_lds_dwordx4 v[226:227], off
	v_lshl_add_u64 v[226:227], s[12:13], 0, v[138:139]
	s_add_i32 m0, s17, 0x2000
	s_nop 0
	global_load_lds_dwordx4 v[226:227], off
	v_lshl_add_u64 v[226:227], v[230:231], 0, s[68:69]
	s_mov_b32 m0, s76
	s_nop 0
	global_load_lds_dwordx4 v[226:227], off
	v_lshl_add_u64 v[226:227], v[232:233], 0, s[68:69]
	s_mov_b32 m0, s77
	s_nop 0
	global_load_lds_dwordx4 v[226:227], off
	s_waitcnt vmcnt(8)
	s_waitcnt lgkmcnt(0)
	s_barrier
	s_waitcnt lgkmcnt(0)
	v_mfma_f32_16x16x32_bf16 v[60:63], v[128:131], v[194:197], v[60:63]
	v_mfma_f32_16x16x32_bf16 v[56:59], v[170:173], v[194:197], v[56:59]
	v_mfma_f32_16x16x32_bf16 v[44:47], v[128:131], v[202:205], v[44:47]
	v_mfma_f32_16x16x32_bf16 v[40:43], v[170:173], v[202:205], v[40:43]
	v_mfma_f32_16x16x32_bf16 v[28:31], v[128:131], v[210:213], v[28:31]
	v_mfma_f32_16x16x32_bf16 v[24:27], v[170:173], v[210:213], v[24:27]
	v_mfma_f32_16x16x32_bf16 v[12:15], v[128:131], v[218:221], v[12:15]
	v_mfma_f32_16x16x32_bf16 v[8:11], v[170:173], v[218:221], v[8:11]
	v_mfma_f32_16x16x32_bf16 v[60:63], v[154:157], v[198:201], v[60:63]
	v_mfma_f32_16x16x32_bf16 v[56:59], v[174:177], v[198:201], v[56:59]
	v_mfma_f32_16x16x32_bf16 v[44:47], v[154:157], v[206:209], v[44:47]
	v_mfma_f32_16x16x32_bf16 v[40:43], v[174:177], v[206:209], v[40:43]
	v_mfma_f32_16x16x32_bf16 v[28:31], v[154:157], v[214:217], v[28:31]
	v_mfma_f32_16x16x32_bf16 v[24:27], v[174:177], v[214:217], v[24:27]
	v_mfma_f32_16x16x32_bf16 v[12:15], v[154:157], v[222:225], v[12:15]
	v_mfma_f32_16x16x32_bf16 v[8:11], v[174:177], v[222:225], v[8:11]
	v_mfma_f32_16x16x32_bf16 v[52:55], v[178:181], v[194:197], v[52:55]
	v_mfma_f32_16x16x32_bf16 v[48:51], v[186:189], v[194:197], v[48:51]
	v_mfma_f32_16x16x32_bf16 v[36:39], v[178:181], v[202:205], v[36:39]
	v_mfma_f32_16x16x32_bf16 v[32:35], v[186:189], v[202:205], v[32:35]
	v_mfma_f32_16x16x32_bf16 v[20:23], v[178:181], v[210:213], v[20:23]
	v_mfma_f32_16x16x32_bf16 v[16:19], v[186:189], v[210:213], v[16:19]
	v_mfma_f32_16x16x32_bf16 v[4:7], v[178:181], v[218:221], v[4:7]
	v_mfma_f32_16x16x32_bf16 v[0:3], v[186:189], v[218:221], v[0:3]
	v_mfma_f32_16x16x32_bf16 v[52:55], v[182:185], v[198:201], v[52:55]
	v_mfma_f32_16x16x32_bf16 v[48:51], v[190:193], v[198:201], v[48:51]
	v_mfma_f32_16x16x32_bf16 v[36:39], v[182:185], v[206:209], v[36:39]
	v_mfma_f32_16x16x32_bf16 v[32:35], v[190:193], v[206:209], v[32:35]
	v_mfma_f32_16x16x32_bf16 v[20:23], v[182:185], v[214:217], v[20:23]
	v_mfma_f32_16x16x32_bf16 v[16:19], v[190:193], v[214:217], v[16:19]
	v_mfma_f32_16x16x32_bf16 v[4:7], v[182:185], v[222:225], v[4:7]
	v_mfma_f32_16x16x32_bf16 v[0:3], v[190:193], v[222:225], v[0:3]
	s_add_i32 s16, s16, 2
	s_add_u32 s10, s10, 0x100
	s_addc_u32 s11, s11, 0
	s_add_u32 vcc_lo, vcc_lo, 0x100
	s_addc_u32 vcc_hi, vcc_hi, 0
	s_cmp_gt_u32 s16, 29
	s_barrier
	s_cbranch_scc0 .LBB0_583
	s_setprio 0
	s_and_b64 vcc, exec, s[18:19]
	s_cbranch_vccnz .LBB0_588
	v_lshl_add_u32 v154, s63, 8, v158
	s_cmp_gt_i32 s81, 31
	s_mov_b64 s[10:11], -1
	s_cbranch_scc1 .LBB0_589
